# v155 + counted vmcnt waits on the gate unit loads (stats first, V/W before staging, u/g-norm/bias at first use)
# speedup vs baseline: 1.0070x; 1.0070x over previous
.LBB0_155:
	s_or_b64 exec, exec, s[28:29]
	s_waitcnt vmcnt(26)
	ds_write_b128 v158, v[12:15] offset:36864
	ds_write_b128 v159, v[16:19] offset:36864
	ds_write_b128 v160, v[28:31] offset:36864
	ds_write_b128 v161, v[32:35] offset:36864
	ds_write_b128 v162, v[44:47] offset:36864
	ds_write_b128 v163, v[48:51] offset:36864
	ds_write_b128 v164, v[60:63] offset:36864
	ds_write_b128 v165, v[64:67] offset:36864
	s_waitcnt lgkmcnt(0)
	s_barrier
	ds_read_b128 v[12:15], v148
	s_mov_b32 s22, 0x5040100
	s_waitcnt lgkmcnt(0)
	v_mul_f32_e32 v12, v68, v12
	v_mul_f32_e32 v13, v69, v13
	v_cndmask_b32_e64 v12, v12, 0, s[62:63]
	v_cndmask_b32_e64 v13, 0, v13, s[64:65]
	v_mul_f32_e32 v14, v70, v14
	v_mul_f32_e32 v15, v71, v15
	v_cndmask_b32_e64 v14, v14, 0, s[66:67]
	v_cndmask_b32_e64 v15, v15, 0, s[2:3]
	v_cvt_pk_bf16_f32 v12, v12, v13
	v_cvt_pk_bf16_f32 v13, v14, v15
	ds_write_b64 v166, v[12:13] offset:1024
	ds_read_b128 v[12:15], v148
	s_waitcnt lgkmcnt(0)
	v_mul_f32_e32 v12, v52, v12
	v_mul_f32_e32 v13, v53, v13
	v_cndmask_b32_e64 v12, v12, 0, s[70:71]
	v_cndmask_b32_e64 v13, 0, v13, s[72:73]
	v_mul_f32_e32 v14, v54, v14
	v_mul_f32_e32 v15, v55, v15
	v_cndmask_b32_e64 v14, v14, 0, s[74:75]
	v_cndmask_b32_e64 v15, v15, 0, s[76:77]
	v_cvt_pk_bf16_f32 v12, v12, v13
	v_cvt_pk_bf16_f32 v13, v14, v15
	ds_write_b64 v167, v[12:13] offset:1024
	ds_read_b128 v[12:15], v148
	s_waitcnt lgkmcnt(0)
	v_mul_f32_e32 v12, v56, v12
	v_mul_f32_e32 v13, v57, v13
	v_cndmask_b32_e64 v12, v12, 0, s[78:79]
	v_cndmask_b32_e64 v13, 0, v13, s[80:81]
	v_mul_f32_e32 v14, v58, v14
	v_mul_f32_e32 v15, v59, v15
	v_cndmask_b32_e64 v14, v14, 0, s[82:83]
	v_cndmask_b32_e64 v15, v15, 0, s[84:85]
	v_cvt_pk_bf16_f32 v12, v12, v13
	v_cvt_pk_bf16_f32 v13, v14, v15
	ds_write_b64 v168, v[12:13] offset:1024
	ds_read_b128 v[12:15], v148
	s_waitcnt lgkmcnt(0)
	v_mul_f32_e32 v12, v36, v12
	v_mul_f32_e32 v13, v37, v13
	v_cndmask_b32_e64 v12, v12, 0, s[86:87]
	v_cndmask_b32_e64 v13, 0, v13, s[88:89]
	v_mul_f32_e32 v14, v38, v14
	v_mul_f32_e32 v15, v39, v15
	v_cndmask_b32_e64 v14, v14, 0, s[90:91]
	v_cndmask_b32_e64 v15, v15, 0, s[92:93]
	v_cvt_pk_bf16_f32 v12, v12, v13
	v_cvt_pk_bf16_f32 v13, v14, v15
	ds_write_b64 v169, v[12:13] offset:1024
	ds_read_b128 v[12:15], v148
	s_waitcnt lgkmcnt(0)
	v_mul_f32_e32 v12, v40, v12
	v_mul_f32_e32 v13, v41, v13
	v_cndmask_b32_e64 v12, v12, 0, s[94:95]
	v_cndmask_b32_e64 v13, 0, v13, s[96:97]
	v_mul_f32_e32 v14, v42, v14
	v_mul_f32_e32 v15, v43, v15
	v_cndmask_b32_e64 v14, v14, 0, s[38:39]
	v_cndmask_b32_e64 v15, v15, 0, s[40:41]
	v_cvt_pk_bf16_f32 v12, v12, v13
	v_cvt_pk_bf16_f32 v13, v14, v15
	ds_write_b64 v170, v[12:13] offset:1024
	ds_read_b128 v[12:15], v148
	s_waitcnt lgkmcnt(0)
	v_mul_f32_e32 v12, v20, v12
	v_mul_f32_e32 v13, v21, v13
	v_cndmask_b32_e64 v12, v12, 0, s[42:43]
	v_cndmask_b32_e64 v13, 0, v13, s[44:45]
	v_mul_f32_e32 v14, v22, v14
	v_mul_f32_e32 v15, v23, v15
	v_cndmask_b32_e64 v14, v14, 0, s[46:47]
	v_cndmask_b32_e64 v15, v15, 0, s[48:49]
	v_cvt_pk_bf16_f32 v12, v12, v13
	v_cvt_pk_bf16_f32 v13, v14, v15
	ds_write_b64 v171, v[12:13] offset:1024
	ds_read_b128 v[12:15], v148
	s_waitcnt lgkmcnt(0)
	v_mul_f32_e32 v12, v24, v12
	v_mul_f32_e32 v13, v25, v13
	v_cndmask_b32_e64 v12, v12, 0, s[50:51]
	v_cndmask_b32_e64 v13, 0, v13, s[52:53]
	v_mul_f32_e32 v14, v26, v14
	v_mul_f32_e32 v15, v27, v15
	v_cndmask_b32_e64 v14, v14, 0, s[54:55]
	v_cndmask_b32_e64 v15, v15, 0, s[56:57]
	v_cvt_pk_bf16_f32 v12, v12, v13
	v_cvt_pk_bf16_f32 v13, v14, v15
	ds_write_b64 v172, v[12:13] offset:1024
	ds_read_b128 v[12:15], v148
	s_waitcnt lgkmcnt(0)
	v_mul_f32_e32 v8, v8, v12
	v_mul_f32_e32 v9, v9, v13
	v_cndmask_b32_e64 v8, v8, 0, s[4:5]
	v_cndmask_b32_e64 v9, 0, v9, s[6:7]
	v_mul_f32_e32 v10, v10, v14
	v_mul_f32_e32 v11, v11, v15
	v_cndmask_b32_e64 v10, v10, 0, s[8:9]
	v_cndmask_b32_e64 v11, v11, 0, s[10:11]
	v_cvt_pk_bf16_f32 v8, v8, v9
	v_cvt_pk_bf16_f32 v9, v10, v11
	ds_write_b64 v173, v[8:9] offset:1024
	s_waitcnt lgkmcnt(0)
	s_barrier
	ds_read_u16 v8, v174 offset:37392
	ds_read_u16 v9, v174 offset:37920
	ds_read_u16 v10, v174 offset:38448
	ds_read_u16 v11, v174 offset:38976
	ds_read_u16 v12, v174 offset:39504
	ds_read_u16 v13, v174 offset:40032
	ds_read_u16 v14, v174 offset:40560
	ds_read_u16 v15, v174 offset:36864
	ds_read_u16 v16, v174 offset:36896
	ds_read_u16 v17, v174 offset:37424
	ds_read_u16 v18, v174 offset:37952
	ds_read_u16 v19, v174 offset:38480
	ds_read_u16 v20, v174 offset:39008
	ds_read_u16 v21, v174 offset:39536
	ds_read_u16 v22, v174 offset:40064
	ds_read_u16 v23, v174 offset:40592
	s_waitcnt lgkmcnt(9)
	v_perm_b32 v27, v14, v13, s22
	v_perm_b32 v26, v12, v11, s22
	v_perm_b32 v25, v10, v9, s22
	s_waitcnt lgkmcnt(8)
	v_perm_b32 v24, v8, v15, s22
	s_waitcnt lgkmcnt(0)
	v_perm_b32 v31, v23, v22, s22
	v_perm_b32 v30, v21, v20, s22
	v_perm_b32 v29, v19, v18, s22
	v_perm_b32 v28, v17, v16, s22
	ds_read_b128 v[32:35], v175 offset:9728
	s_waitcnt lgkmcnt(0)
	v_mfma_f32_16x16x32_bf16 v[36:39], v[24:27], v[32:35], 0
	ds_read_b128 v[8:11], v175 offset:1024
	ds_read_b128 v[12:15], v175 offset:5376
	v_mfma_f32_16x16x32_bf16 v[40:43], v[28:31], v[32:35], 0
	ds_read_b128 v[32:35], v175 offset:14080
	s_waitcnt lgkmcnt(0)
	v_mfma_f32_16x16x32_bf16 v[44:47], v[24:27], v[32:35], 0
	v_mfma_f32_16x16x32_bf16 v[48:51], v[28:31], v[32:35], 0
	ds_read_b128 v[32:35], v175 offset:18432
	s_waitcnt lgkmcnt(0)
	v_mfma_f32_16x16x32_bf16 v[52:55], v[24:27], v[32:35], 0
	v_mfma_f32_16x16x32_bf16 v[56:59], v[28:31], v[32:35], 0
	ds_read_b128 v[32:35], v175 offset:22784
	s_waitcnt lgkmcnt(0)
	v_mfma_f32_16x16x32_bf16 v[60:63], v[24:27], v[32:35], 0
	v_mfma_f32_16x16x32_bf16 v[64:67], v[28:31], v[32:35], 0
	ds_read_b128 v[32:35], v175 offset:27136
	s_waitcnt lgkmcnt(0)
	v_mfma_f32_16x16x32_bf16 v[68:71], v[24:27], v[32:35], 0
	v_mfma_f32_16x16x32_bf16 v[72:75], v[28:31], v[32:35], 0
	ds_read_b128 v[32:35], v175 offset:31488
	v_mfma_f32_16x16x32_bf16 v[16:19], v[24:27], v[8:11], 0
	v_mfma_f32_16x16x32_bf16 v[8:11], v[28:31], v[8:11], 0
	v_mfma_f32_16x16x32_bf16 v[20:23], v[24:27], v[12:15], 0
	s_nop 5
	s_waitcnt vmcnt(0)
	v_fma_f32 v16, v4, v16, v198
	v_fma_f32 v17, v5, v17, v198
	v_fma_f32 v8, v0, v8, v198
	v_mfma_f32_16x16x32_bf16 v[12:15], v[28:31], v[12:15], 0
	s_waitcnt lgkmcnt(0)
	v_mfma_f32_16x16x32_bf16 v[76:79], v[24:27], v[32:35], 0
	v_fma_f32 v20, v4, v20, v197
	v_mfma_f32_16x16x32_bf16 v[80:83], v[28:31], v[32:35], 0
	ds_read_u16 v24, v174 offset:53760
	ds_read_u16 v25, v174 offset:54288
	ds_read_u16 v26, v174 offset:54816
	ds_read_u16 v27, v174 offset:55344
	ds_read_u16 v28, v174 offset:55872
	ds_read_u16 v29, v174 offset:56400
	ds_read_u16 v30, v174 offset:56928
	ds_read_u16 v31, v174 offset:57456
	ds_read_u16 v32, v174 offset:53792
	ds_read_u16 v33, v174 offset:54320
	ds_read_u16 v34, v174 offset:54848
	ds_read_u16 v35, v174 offset:55376
	ds_read_u16 v199, v174 offset:55904
	ds_read_u16 v204, v174 offset:56432
	ds_read_u16 v214, v174 offset:56960
	ds_read_u16 v215, v174 offset:57488
	s_waitcnt lgkmcnt(8)
	v_perm_b32 v213, v31, v30, s22
	v_perm_b32 v212, v29, v28, s22
	v_perm_b32 v211, v27, v26, s22
	v_perm_b32 v210, v25, v24, s22
	s_waitcnt lgkmcnt(0)
	v_perm_b32 v217, v215, v214, s22
	v_perm_b32 v216, v204, v199, s22
	v_perm_b32 v215, v35, v34, s22
	v_perm_b32 v214, v33, v32, s22
	ds_read_b128 v[24:27], v175 offset:9792
	ds_read_b128 v[28:31], v175 offset:14144
	s_waitcnt lgkmcnt(1)
	v_mfma_f32_16x16x32_bf16 v[32:35], v[210:213], v[24:27], v[36:39]
	v_mfma_f32_16x16x32_bf16 v[24:27], v[214:217], v[24:27], v[40:43]
	s_nop 2
	ds_read_b128 v[40:43], v175 offset:18496
	s_waitcnt lgkmcnt(1)
	v_mfma_f32_16x16x32_bf16 v[36:39], v[210:213], v[28:31], v[44:47]
	s_waitcnt lgkmcnt(0)
	v_mfma_f32_16x16x32_bf16 v[44:47], v[210:213], v[40:43], v[52:55]
	s_nop 2
	ds_read_b128 v[52:55], v175 offset:22848
	v_mfma_f32_16x16x32_bf16 v[28:31], v[214:217], v[28:31], v[48:51]
	s_waitcnt lgkmcnt(0)
	v_mfma_f32_16x16x32_bf16 v[48:51], v[210:213], v[52:55], v[60:63]
	s_nop 2
	ds_read_b128 v[60:63], v175 offset:27200
	v_mfma_f32_16x16x32_bf16 v[40:43], v[214:217], v[40:43], v[56:59]
	s_waitcnt lgkmcnt(0)
	v_mfma_f32_16x16x32_bf16 v[56:59], v[210:213], v[60:63], v[68:71]
	s_nop 2
	ds_read_b128 v[68:71], v175 offset:31552
	v_mfma_f32_16x16x32_bf16 v[52:55], v[214:217], v[52:55], v[64:67]
	v_mfma_f32_16x16x32_bf16 v[60:63], v[214:217], v[60:63], v[72:75]
	s_waitcnt lgkmcnt(0)
	v_mfma_f32_16x16x32_bf16 v[64:67], v[210:213], v[68:71], v[76:79]
	v_mfma_f32_16x16x32_bf16 v[68:71], v[214:217], v[68:71], v[80:83]
	ds_read_u16 v72, v176 offset:36864
	s_nop 0
	ds_read_u16 v76, v176 offset:36896
	ds_read_u16 v77, v177 offset:36864
	ds_read_u16 v80, v177 offset:36896
	ds_read_u16 v73, v178 offset:36864
	ds_read_u16 v81, v178 offset:36896
	ds_read_u16 v78, v179 offset:36864
	ds_read_u16 v82, v179 offset:36896
	ds_read_u16 v74, v180 offset:36864
	ds_read_u16 v83, v180 offset:36896
	ds_read_u16 v79, v181 offset:36864
	ds_read_u16 v199, v181 offset:36896
	ds_read_u16 v75, v182 offset:36864
	ds_read_u16 v204, v182 offset:36896
	ds_read_u16 v210, v183 offset:36864
	ds_read_u16 v211, v183 offset:36896
	s_waitcnt lgkmcnt(5)
	v_perm_b32 v74, v79, v74, s22
	v_perm_b32 v73, v78, v73, s22
	v_perm_b32 v72, v77, v72, s22
	s_waitcnt lgkmcnt(1)
	v_perm_b32 v75, v210, v75, s22
	s_waitcnt lgkmcnt(0)
	v_perm_b32 v79, v211, v204, s22
	v_perm_b32 v78, v199, v83, s22
	v_perm_b32 v77, v82, v81, s22
	v_perm_b32 v76, v80, v76, s22
	ds_read_b128 v[80:83], v175 offset:18560
	ds_read_b128 v[210:213], v175 offset:22912
	s_waitcnt lgkmcnt(1)
	v_mfma_f32_16x16x32_bf16 v[44:47], v[72:75], v[80:83], v[44:47]
	v_mfma_f32_16x16x32_bf16 v[40:43], v[76:79], v[80:83], v[40:43]
	s_waitcnt lgkmcnt(0)
	v_mfma_f32_16x16x32_bf16 v[80:83], v[72:75], v[210:213], v[48:51]
	v_mfma_f32_16x16x32_bf16 v[48:51], v[76:79], v[210:213], v[52:55]
	s_nop 2
	ds_read_b128 v[52:55], v175 offset:27264
	s_waitcnt lgkmcnt(0)
	v_mfma_f32_16x16x32_bf16 v[56:59], v[72:75], v[52:55], v[56:59]
	v_mfma_f32_16x16x32_bf16 v[52:55], v[76:79], v[52:55], v[60:63]
	s_nop 2
	ds_read_b128 v[60:63], v175 offset:31616
	s_waitcnt lgkmcnt(0)
	v_mfma_f32_16x16x32_bf16 v[64:67], v[72:75], v[60:63], v[64:67]
	v_mfma_f32_16x16x32_bf16 v[60:63], v[76:79], v[60:63], v[68:71]
	s_nop 2
	ds_read_u16 v68, v184 offset:36864
	ds_read_u16 v72, v184 offset:36896
	ds_read_u16 v73, v185 offset:36864
	ds_read_u16 v76, v185 offset:36896
	ds_read_u16 v69, v186 offset:36864
	ds_read_u16 v77, v186 offset:36896
	ds_read_u16 v74, v187 offset:36864
	ds_read_u16 v78, v187 offset:36896
	ds_read_u16 v70, v188 offset:36864
	ds_read_u16 v79, v188 offset:36896
	ds_read_u16 v75, v189 offset:36864
	ds_read_u16 v199, v189 offset:36896
	ds_read_u16 v71, v190 offset:36864
	ds_read_u16 v204, v190 offset:36896
	ds_read_u16 v210, v191 offset:36864
	ds_read_u16 v211, v191 offset:36896
	s_waitcnt lgkmcnt(5)
	v_perm_b32 v70, v75, v70, s22
	v_perm_b32 v69, v74, v69, s22
	v_perm_b32 v68, v73, v68, s22
	s_waitcnt lgkmcnt(1)
	v_perm_b32 v71, v210, v71, s22
	v_perm_b32 v74, v199, v79, s22
	v_perm_b32 v73, v78, v77, s22
	v_perm_b32 v72, v76, v72, s22
	ds_read_b128 v[76:79], v175 offset:27328
	s_waitcnt lgkmcnt(1)
	v_perm_b32 v75, v211, v204, s22
	s_waitcnt lgkmcnt(0)
	v_mfma_f32_16x16x32_bf16 v[210:213], v[68:71], v[76:79], v[56:59]
	s_nop 2
	ds_read_b128 v[56:59], v175 offset:31680
	v_readlane_b32 s22, v254, 34
	s_add_i32 s21, s21, s22
	s_waitcnt lgkmcnt(0)
	v_mfma_f32_16x16x32_bf16 v[64:67], v[68:71], v[56:59], v[64:67]
	v_lshlrev_b32_e32 v68, 16, v141
	v_and_b32_e32 v69, 0xffff0000, v141
	s_cmpk_lt_i32 s21, 0x200
	v_mfma_f32_16x16x32_bf16 v[56:59], v[72:75], v[56:59], v[60:63]
	v_readlane_b32 s22, v252, 9
	s_cselect_b64 s[28:29], -1, 0
	s_cmp_lt_u32 s25, s22
	v_lshlrev_b32_e32 v62, 16, v140
	v_and_b32_e32 v63, 0xffff0000, v140
	v_mul_f32_e32 v16, v16, v62
	v_mul_f32_e32 v17, v17, v63
	v_cvt_pk_bf16_f32 v16, v16, v17
	v_fma_f32 v17, v6, v18, v198
	v_fma_f32 v18, v7, v19, v198
	v_lshl_add_u64 v[60:61], v[136:137], 1, s[34:35]
	v_mul_f32_e32 v17, v17, v68
	v_mul_f32_e32 v18, v18, v69
	v_cvt_pk_bf16_f32 v17, v17, v18
	v_lshl_add_u64 v[18:19], v[60:61], 0, v[108:109]
	v_bfe_u32 v255, v234, 4, 1
	v_mul_u32_u24_e32 v255, 24, v255
	v_mov_b32_e32 v218, v16
	v_mov_b32_e32 v219, v17
	v_lshlrev_b32_e32 v16, 16, v138
	v_and_b32_e32 v17, 0xffff0000, v138
	v_mul_f32_e32 v16, v20, v16
	v_fma_f32 v20, v5, v21, v197
	v_mul_f32_e32 v17, v20, v17
	v_lshlrev_b32_e32 v18, 16, v139
	v_cvt_pk_bf16_f32 v16, v16, v17
	v_fma_f32 v17, v6, v22, v197
	v_and_b32_e32 v19, 0xffff0000, v139
	v_mul_f32_e32 v17, v17, v18
	v_fma_f32 v18, v7, v23, v197
	v_mul_f32_e32 v18, v18, v19
	v_cvt_pk_bf16_f32 v17, v17, v18
	v_lshl_add_u64 v[18:19], v[60:61], 0, v[104:105]
	v_mov_b32_e32 v220, v16
	v_mov_b32_e32 v221, v17
	v_lshlrev_b32_e32 v16, 16, v134
	v_fma_f32 v20, v4, v32, v196
	v_and_b32_e32 v17, 0xffff0000, v134
	v_mul_f32_e32 v16, v20, v16
	v_fma_f32 v20, v5, v33, v196
	v_mul_f32_e32 v17, v20, v17
	v_lshlrev_b32_e32 v18, 16, v135
	v_cvt_pk_bf16_f32 v16, v16, v17
	v_fma_f32 v17, v6, v34, v196
	v_and_b32_e32 v19, 0xffff0000, v135
	v_mul_f32_e32 v17, v17, v18
	v_fma_f32 v18, v7, v35, v196
	v_mul_f32_e32 v18, v18, v19
	v_cvt_pk_bf16_f32 v17, v17, v18
	v_lshl_add_u64 v[18:19], v[60:61], 0, v[102:103]
	v_mov_b32_e32 v222, v16
	v_mov_b32_e32 v223, v17
	v_lshlrev_b32_e32 v16, 16, v130
	v_fma_f32 v20, v4, v36, v195
	v_and_b32_e32 v17, 0xffff0000, v130
	v_mul_f32_e32 v16, v20, v16
	v_fma_f32 v20, v5, v37, v195
	v_mul_f32_e32 v17, v20, v17
	v_lshlrev_b32_e32 v18, 16, v131
	v_cvt_pk_bf16_f32 v16, v16, v17
	v_fma_f32 v17, v6, v38, v195
	v_and_b32_e32 v19, 0xffff0000, v131
	v_mul_f32_e32 v17, v17, v18
	v_fma_f32 v18, v7, v39, v195
	v_mul_f32_e32 v18, v18, v19
	v_cvt_pk_bf16_f32 v17, v17, v18
	v_lshl_add_u64 v[18:19], v[60:61], 0, v[98:99]
	v_mov_b32_e32 v224, v16
	v_mov_b32_e32 v225, v17
	v_lshlrev_b32_e32 v16, 16, v132
	v_fma_f32 v20, v4, v44, v194
	v_and_b32_e32 v17, 0xffff0000, v132
	v_mul_f32_e32 v16, v20, v16
	v_fma_f32 v20, v5, v45, v194
	v_mul_f32_e32 v17, v20, v17
	v_lshlrev_b32_e32 v18, 16, v133
	v_cvt_pk_bf16_f32 v16, v16, v17
	v_fma_f32 v17, v6, v46, v194
	v_and_b32_e32 v19, 0xffff0000, v133
	v_mul_f32_e32 v17, v17, v18
	v_fma_f32 v18, v7, v47, v194
	v_mul_f32_e32 v18, v18, v19
	v_cvt_pk_bf16_f32 v17, v17, v18
	v_lshl_add_u64 v[18:19], v[60:61], 0, v[96:97]
	v_mov_b32_e32 v226, v16
	v_mov_b32_e32 v227, v17
	v_lshlrev_b32_e32 v16, 16, v128
	v_fma_f32 v20, v4, v80, v193
	v_and_b32_e32 v17, 0xffff0000, v128
	v_mul_f32_e32 v16, v20, v16
	v_fma_f32 v20, v5, v81, v193
	v_mul_f32_e32 v17, v20, v17
	v_lshlrev_b32_e32 v18, 16, v129
	v_cvt_pk_bf16_f32 v16, v16, v17
	v_fma_f32 v17, v6, v82, v193
	v_and_b32_e32 v19, 0xffff0000, v129
	v_mul_f32_e32 v17, v17, v18
	v_fma_f32 v18, v7, v83, v193
	v_mul_f32_e32 v18, v18, v19
	v_cvt_pk_bf16_f32 v17, v17, v18
	v_lshl_add_u64 v[18:19], v[60:61], 0, v[94:95]
	v_mov_b32_e32 v228, v16
	v_mov_b32_e32 v229, v17
	v_lshlrev_b32_e32 v16, 16, v126
	v_fma_f32 v20, v4, v210, v192
	v_and_b32_e32 v17, 0xffff0000, v126
	v_mul_f32_e32 v16, v20, v16
	v_fma_f32 v20, v5, v211, v192
	v_mul_f32_e32 v17, v20, v17
	v_lshlrev_b32_e32 v18, 16, v127
	v_cvt_pk_bf16_f32 v16, v16, v17
	v_fma_f32 v17, v6, v212, v192
	v_and_b32_e32 v19, 0xffff0000, v127
	v_mul_f32_e32 v17, v17, v18
	v_fma_f32 v18, v7, v213, v192
	v_mul_f32_e32 v18, v18, v19
	v_cvt_pk_bf16_f32 v17, v17, v18
	v_lshl_add_u64 v[18:19], v[60:61], 0, v[92:93]
	v_mov_b32_e32 v230, v16
	v_mov_b32_e32 v231, v17
	v_lshlrev_b32_e32 v16, 16, v124
	v_and_b32_e32 v17, 0xffff0000, v124
	v_fma_f32 v4, v4, v64, v113
	v_fma_f32 v5, v5, v65, v113
	v_mul_f32_e32 v4, v4, v16
	v_mul_f32_e32 v5, v5, v17
	v_lshlrev_b32_e32 v18, 16, v125
	v_and_b32_e32 v19, 0xffff0000, v125
	v_cvt_pk_bf16_f32 v4, v4, v5
	v_fma_f32 v5, v6, v66, v113
	v_fma_f32 v6, v7, v67, v113
	v_mul_f32_e32 v5, v5, v18
	v_mul_f32_e32 v6, v6, v19
	v_cvt_pk_bf16_f32 v5, v5, v6
	v_or_b32_e32 v6, 0x70, v112
	v_ashrrev_i32_e32 v7, 31, v6
	v_lshlrev_b64 v[6:7], 12, v[6:7]
	v_lshl_add_u64 v[16:17], v[60:61], 0, v[6:7]
	v_mov_b32_e32 v232, v4
	v_mov_b32_e32 v233, v5
	v_lshlrev_b32_e32 v4, 16, v122
	v_and_b32_e32 v5, 0xffff0000, v122
	v_mul_f32_e32 v4, v8, v4
	v_fma_f32 v8, v1, v9, v198
	v_mul_f32_e32 v5, v8, v5
	v_lshlrev_b32_e32 v16, 16, v123
	v_and_b32_e32 v17, 0xffff0000, v123
	v_cvt_pk_bf16_f32 v4, v4, v5
	v_fma_f32 v5, v2, v10, v198
	v_fmac_f32_e32 v198, v3, v11
	v_mul_f32_e32 v5, v5, v16
	v_mul_f32_e32 v8, v198, v17
	v_cvt_pk_bf16_f32 v5, v5, v8
	v_lshl_add_u64 v[8:9], s[34:35], 0, v[108:109]
	v_lshl_add_u64 v[8:9], v[8:9], 0, v[90:91]
	v_mov_b32_e32 v214, v218
	v_mov_b32_e32 v215, v219
	v_mov_b32_e32 v216, v4
	v_mov_b32_e32 v217, v5
	v_add_u32_e32 v8, v8, v255
	s_nop 1
	v_permlane16_swap_b32_e32 v214, v216
	v_permlane16_swap_b32_e32 v215, v217
	global_store_dwordx4 v[8:9], v[214:217], off offset:-32
	v_lshlrev_b32_e32 v4, 16, v120
	v_fma_f32 v10, v0, v12, v197
	v_and_b32_e32 v5, 0xffff0000, v120
	v_mul_f32_e32 v4, v10, v4
	v_fma_f32 v10, v1, v13, v197
	v_mul_f32_e32 v5, v10, v5
	v_lshlrev_b32_e32 v8, 16, v121
	v_and_b32_e32 v9, 0xffff0000, v121
	v_cvt_pk_bf16_f32 v4, v4, v5
	v_fma_f32 v5, v2, v14, v197
	v_fmac_f32_e32 v197, v3, v15
	v_mul_f32_e32 v5, v5, v8
	v_mul_f32_e32 v8, v197, v9
	v_cvt_pk_bf16_f32 v5, v5, v8
	v_lshl_add_u64 v[8:9], s[34:35], 0, v[104:105]
	v_lshl_add_u64 v[8:9], v[8:9], 0, v[90:91]
	v_mov_b32_e32 v214, v220
	v_mov_b32_e32 v215, v221
	v_mov_b32_e32 v216, v4
	v_mov_b32_e32 v217, v5
	v_add_u32_e32 v8, v8, v255
	s_nop 1
	v_permlane16_swap_b32_e32 v214, v216
	v_permlane16_swap_b32_e32 v215, v217
	global_store_dwordx4 v[8:9], v[214:217], off offset:-32
	v_lshlrev_b32_e32 v4, 16, v118
	v_fma_f32 v10, v0, v24, v196
	v_and_b32_e32 v5, 0xffff0000, v118
	v_mul_f32_e32 v4, v10, v4
	v_fma_f32 v10, v1, v25, v196
	v_mul_f32_e32 v5, v10, v5
	v_lshlrev_b32_e32 v8, 16, v119
	v_and_b32_e32 v9, 0xffff0000, v119
	v_cvt_pk_bf16_f32 v4, v4, v5
	v_fma_f32 v5, v2, v26, v196
	v_fmac_f32_e32 v196, v3, v27
	v_mul_f32_e32 v5, v5, v8
	v_mul_f32_e32 v8, v196, v9
	v_cvt_pk_bf16_f32 v5, v5, v8
	v_lshl_add_u64 v[8:9], s[34:35], 0, v[102:103]
	v_lshl_add_u64 v[8:9], v[8:9], 0, v[90:91]
	v_mov_b32_e32 v214, v222
	v_mov_b32_e32 v215, v223
	v_mov_b32_e32 v216, v4
	v_mov_b32_e32 v217, v5
	v_add_u32_e32 v8, v8, v255
	s_nop 1
	v_permlane16_swap_b32_e32 v214, v216
	v_permlane16_swap_b32_e32 v215, v217
	global_store_dwordx4 v[8:9], v[214:217], off offset:-32
	v_lshlrev_b32_e32 v4, 16, v116
	v_fma_f32 v10, v0, v28, v195
	v_and_b32_e32 v5, 0xffff0000, v116
	v_mul_f32_e32 v4, v10, v4
	v_fma_f32 v10, v1, v29, v195
	v_mul_f32_e32 v5, v10, v5
	v_lshlrev_b32_e32 v8, 16, v117
	v_and_b32_e32 v9, 0xffff0000, v117
	v_cvt_pk_bf16_f32 v4, v4, v5
	v_fma_f32 v5, v2, v30, v195
	v_fmac_f32_e32 v195, v3, v31
	v_mul_f32_e32 v5, v5, v8
	v_mul_f32_e32 v8, v195, v9
	v_cvt_pk_bf16_f32 v5, v5, v8
	v_lshl_add_u64 v[8:9], s[34:35], 0, v[98:99]
	v_lshl_add_u64 v[8:9], v[8:9], 0, v[90:91]
	v_mov_b32_e32 v214, v224
	v_mov_b32_e32 v215, v225
	v_mov_b32_e32 v216, v4
	v_mov_b32_e32 v217, v5
	v_add_u32_e32 v8, v8, v255
	s_nop 1
	v_permlane16_swap_b32_e32 v214, v216
	v_permlane16_swap_b32_e32 v215, v217
	global_store_dwordx4 v[8:9], v[214:217], off offset:-32
	v_lshlrev_b32_e32 v4, 16, v114
	v_fma_f32 v10, v0, v40, v194
	v_and_b32_e32 v5, 0xffff0000, v114
	v_mul_f32_e32 v4, v10, v4
	v_fma_f32 v10, v1, v41, v194
	v_mul_f32_e32 v5, v10, v5
	v_lshlrev_b32_e32 v8, 16, v115
	v_and_b32_e32 v9, 0xffff0000, v115
	v_cvt_pk_bf16_f32 v4, v4, v5
	v_fma_f32 v5, v2, v42, v194
	v_fmac_f32_e32 v194, v3, v43
	v_mul_f32_e32 v5, v5, v8
	v_mul_f32_e32 v8, v194, v9
	v_cvt_pk_bf16_f32 v5, v5, v8
	v_lshl_add_u64 v[8:9], s[34:35], 0, v[96:97]
	v_lshl_add_u64 v[8:9], v[8:9], 0, v[90:91]
	v_mov_b32_e32 v214, v226
	v_mov_b32_e32 v215, v227
	v_mov_b32_e32 v216, v4
	v_mov_b32_e32 v217, v5
	v_add_u32_e32 v8, v8, v255
	s_nop 1
	v_permlane16_swap_b32_e32 v214, v216
	v_permlane16_swap_b32_e32 v215, v217
	global_store_dwordx4 v[8:9], v[214:217], off offset:-32
	v_lshlrev_b32_e32 v4, 16, v110
	v_fma_f32 v10, v0, v48, v193
	v_and_b32_e32 v5, 0xffff0000, v110
	v_mul_f32_e32 v4, v10, v4
	v_fma_f32 v10, v1, v49, v193
	v_mul_f32_e32 v5, v10, v5
	v_mfma_f32_16x16x32_bf16 v[52:55], v[72:75], v[76:79], v[52:55]
	v_lshlrev_b32_e32 v8, 16, v111
	v_and_b32_e32 v9, 0xffff0000, v111
	v_cvt_pk_bf16_f32 v4, v4, v5
	v_fma_f32 v5, v2, v50, v193
	v_fmac_f32_e32 v193, v3, v51
	v_mul_f32_e32 v5, v5, v8
	v_mul_f32_e32 v8, v193, v9
	v_cvt_pk_bf16_f32 v5, v5, v8
	v_lshl_add_u64 v[8:9], s[34:35], 0, v[94:95]
	v_lshl_add_u64 v[8:9], v[8:9], 0, v[90:91]
	v_mov_b32_e32 v214, v228
	v_mov_b32_e32 v215, v229
	v_mov_b32_e32 v216, v4
	v_mov_b32_e32 v217, v5
	v_add_u32_e32 v8, v8, v255
	s_nop 1
	v_permlane16_swap_b32_e32 v214, v216
	v_permlane16_swap_b32_e32 v215, v217
	global_store_dwordx4 v[8:9], v[214:217], off offset:-32
	v_lshlrev_b32_e32 v4, 16, v106
	v_fma_f32 v10, v0, v52, v192
	v_and_b32_e32 v5, 0xffff0000, v106
	v_mul_f32_e32 v4, v10, v4
	v_fma_f32 v10, v1, v53, v192
	v_mul_f32_e32 v5, v10, v5
	v_lshlrev_b32_e32 v8, 16, v107
	v_and_b32_e32 v9, 0xffff0000, v107
	v_cvt_pk_bf16_f32 v4, v4, v5
	v_fma_f32 v5, v2, v54, v192
	v_fmac_f32_e32 v192, v3, v55
	v_mul_f32_e32 v5, v5, v8
	v_mul_f32_e32 v8, v192, v9
	v_cvt_pk_bf16_f32 v5, v5, v8
	v_lshl_add_u64 v[8:9], s[34:35], 0, v[92:93]
	v_lshl_add_u64 v[8:9], v[8:9], 0, v[90:91]
	v_mov_b32_e32 v214, v230
	v_mov_b32_e32 v215, v231
	v_mov_b32_e32 v216, v4
	v_mov_b32_e32 v217, v5
	v_add_u32_e32 v8, v8, v255
	s_nop 1
	v_permlane16_swap_b32_e32 v214, v216
	v_permlane16_swap_b32_e32 v215, v217
	global_store_dwordx4 v[8:9], v[214:217], off offset:-32
	v_lshlrev_b32_e32 v4, 16, v100
	v_and_b32_e32 v5, 0xffff0000, v100
	v_fma_f32 v0, v0, v56, v113
	v_fma_f32 v1, v1, v57, v113
	v_mul_f32_e32 v0, v0, v4
	v_mul_f32_e32 v1, v1, v5
	v_lshlrev_b32_e32 v8, 16, v101
	v_and_b32_e32 v9, 0xffff0000, v101
	v_cvt_pk_bf16_f32 v0, v0, v1
	v_fma_f32 v1, v2, v58, v113
	v_fmac_f32_e32 v113, v3, v59
	v_mul_f32_e32 v1, v1, v8
	v_mul_f32_e32 v2, v113, v9
	s_cselect_b64 vcc, -1, 0
	v_cvt_pk_bf16_f32 v1, v1, v2
	v_lshl_add_u64 v[2:3], s[34:35], 0, v[6:7]
	s_and_b64 s[28:29], s[28:29], vcc
	v_readlane_b32 s22, v254, 35
	v_lshl_add_u64 v[2:3], v[2:3], 0, v[90:91]
	s_add_i32 s20, s20, s22
	s_add_i32 s25, s25, 1
	s_andn2_b64 vcc, exec, s[28:29]
	v_mov_b32_e32 v214, v232
	v_mov_b32_e32 v215, v233
	v_mov_b32_e32 v216, v0
	v_mov_b32_e32 v217, v1
	v_add_u32_e32 v2, v2, v255
	s_nop 1
	v_permlane16_swap_b32_e32 v214, v216
	v_permlane16_swap_b32_e32 v215, v217
	global_store_dwordx4 v[2:3], v[214:217], off offset:-32
	s_barrier
	s_cbranch_vccnz .LBB0_158
.LBB0_156:
	s_and_b32 s29, s20, 0xffffff80
	v_add_u32_e32 v0, s29, v143
	v_ashrrev_i32_e32 v1, 31, v0
	s_and_b32 s28, s21, 7
	v_lshlrev_b64 v[0:1], 7, v[0:1]
	v_add_u32_e32 v2, s29, v149
	v_add_u32_e32 v4, s29, v150
	v_lshl_add_u64 v[0:1], v[84:85], 0, v[0:1]
	s_lshl_b32 s22, s28, 9
	v_ashrrev_i32_e32 v3, 31, v2
	v_ashrrev_i32_e32 v5, 31, v4
	global_load_dwordx4 v[72:75], v[0:1], off offset:16
	global_load_dwordx4 v[76:79], v[0:1], off
	v_lshl_add_u64 v[0:1], v[86:87], 0, s[22:23]
	v_lshlrev_b64 v[2:3], 12, v[2:3]
	v_lshlrev_b64 v[4:5], 12, v[4:5]
	v_lshl_add_u64 v[2:3], v[0:1], 0, v[2:3]
	v_lshl_add_u64 v[4:5], v[0:1], 0, v[4:5]
	global_load_dwordx4 v[12:15], v[2:3], off
	global_load_dwordx4 v[16:19], v[4:5], off
	v_add_u32_e32 v2, s29, v151
	v_add_u32_e32 v4, s29, v152
	v_ashrrev_i32_e32 v3, 31, v2
	v_ashrrev_i32_e32 v5, 31, v4
	v_lshlrev_b64 v[2:3], 12, v[2:3]
	v_lshlrev_b64 v[4:5], 12, v[4:5]
	v_lshl_add_u64 v[2:3], v[0:1], 0, v[2:3]
	v_lshl_add_u64 v[4:5], v[0:1], 0, v[4:5]
	global_load_dwordx4 v[28:31], v[2:3], off
	global_load_dwordx4 v[32:35], v[4:5], off
	v_add_u32_e32 v2, s29, v153
	v_add_u32_e32 v4, s29, v154
	v_ashrrev_i32_e32 v3, 31, v2
	v_ashrrev_i32_e32 v5, 31, v4
	v_lshlrev_b64 v[2:3], 12, v[2:3]
	v_lshlrev_b64 v[4:5], 12, v[4:5]
	v_lshl_add_u64 v[2:3], v[0:1], 0, v[2:3]
	v_lshl_add_u64 v[4:5], v[0:1], 0, v[4:5]
	global_load_dwordx4 v[44:47], v[2:3], off
	global_load_dwordx4 v[48:51], v[4:5], off
	v_add_u32_e32 v2, s29, v155
	v_add_u32_e32 v4, s29, v156
	v_ashrrev_i32_e32 v3, 31, v2
	v_ashrrev_i32_e32 v5, 31, v4
	v_lshlrev_b64 v[2:3], 12, v[2:3]
	v_lshlrev_b64 v[4:5], 12, v[4:5]
	v_lshl_add_u64 v[2:3], v[0:1], 0, v[2:3]
	v_lshl_add_u64 v[0:1], v[0:1], 0, v[4:5]
	s_lshl_b32 s22, s28, 7
	global_load_dwordx4 v[60:63], v[2:3], off
	global_load_dwordx4 v[64:67], v[0:1], off
	v_add_u32_e32 v0, s22, v149
	v_add_u32_e32 v2, s22, v150
	v_ashrrev_i32_e32 v1, 31, v0
	v_ashrrev_i32_e32 v3, 31, v2
	v_lshlrev_b64 v[0:1], 9, v[0:1]
	v_lshlrev_b64 v[2:3], 9, v[2:3]
	v_lshl_add_u64 v[0:1], v[88:89], 0, v[0:1]
	v_lshl_add_u64 v[2:3], v[88:89], 0, v[2:3]
	global_load_dwordx4 v[68:71], v[0:1], off
	global_load_dwordx4 v[52:55], v[2:3], off
	v_add_u32_e32 v0, s22, v151
	v_add_u32_e32 v2, s22, v152
	v_ashrrev_i32_e32 v1, 31, v0
	v_ashrrev_i32_e32 v3, 31, v2
	v_lshlrev_b64 v[0:1], 9, v[0:1]
	v_lshlrev_b64 v[2:3], 9, v[2:3]
	v_lshl_add_u64 v[0:1], v[88:89], 0, v[0:1]
	v_lshl_add_u64 v[2:3], v[88:89], 0, v[2:3]
	global_load_dwordx4 v[56:59], v[0:1], off
	global_load_dwordx4 v[36:39], v[2:3], off
	v_add_u32_e32 v0, s22, v153
	v_add_u32_e32 v2, s22, v154
	v_ashrrev_i32_e32 v1, 31, v0
	v_ashrrev_i32_e32 v3, 31, v2
	v_lshlrev_b64 v[0:1], 9, v[0:1]
	v_lshlrev_b64 v[2:3], 9, v[2:3]
	v_lshl_add_u64 v[0:1], v[88:89], 0, v[0:1]
	v_lshl_add_u64 v[2:3], v[88:89], 0, v[2:3]
	global_load_dwordx4 v[40:43], v[0:1], off
	global_load_dwordx4 v[20:23], v[2:3], off
	v_add_u32_e32 v0, s22, v155
	v_add_u32_e32 v2, s22, v156
	v_ashrrev_i32_e32 v1, 31, v0
	v_ashrrev_i32_e32 v3, 31, v2
	v_or_b32_e32 v112, s29, v142
	v_lshlrev_b64 v[0:1], 9, v[0:1]
	v_lshlrev_b64 v[2:3], 9, v[2:3]
	v_lshl_add_u32 v136, s28, 8, v144
	v_or_b32_e32 v80, 32, v112
	v_lshl_add_u64 v[0:1], v[88:89], 0, v[0:1]
	v_lshl_add_u64 v[2:3], v[88:89], 0, v[2:3]
	v_ashrrev_i32_e32 v113, 31, v112
	v_ashrrev_i32_e32 v137, 31, v136
	v_or_b32_e32 v6, 16, v112
	v_ashrrev_i32_e32 v81, 31, v80
	v_or_b32_e32 v82, 48, v112
	global_load_dwordx4 v[24:27], v[0:1], off
	global_load_dwordx4 v[8:11], v[2:3], off
	v_lshlrev_b64 v[108:109], 12, v[112:113]
	v_lshl_add_u64 v[2:3], v[136:137], 1, s[26:27]
	v_ashrrev_i32_e32 v7, 31, v6
	v_lshlrev_b64 v[102:103], 12, v[80:81]
	v_ashrrev_i32_e32 v83, 31, v82
	v_lshl_add_u64 v[4:5], v[2:3], 0, v[108:109]
	v_lshlrev_b64 v[104:105], 12, v[6:7]
	v_lshl_add_u64 v[80:81], v[2:3], 0, v[102:103]
	v_lshlrev_b64 v[98:99], 12, v[82:83]
	v_lshl_add_u64 v[6:7], v[2:3], 0, v[104:105]
	v_lshl_add_u64 v[82:83], v[2:3], 0, v[98:99]
	global_load_dwordx2 v[140:141], v[4:5], off
	global_load_dwordx2 v[138:139], v[6:7], off
	global_load_dwordx2 v[134:135], v[80:81], off
	global_load_dwordx2 v[130:131], v[82:83], off
	v_or_b32_e32 v4, 64, v112
	v_or_b32_e32 v80, 0x60, v112
	v_ashrrev_i32_e32 v5, 31, v4
	v_or_b32_e32 v6, 0x50, v112
	v_ashrrev_i32_e32 v81, 31, v80
	v_or_b32_e32 v82, s20, v157
	v_lshlrev_b64 v[96:97], 12, v[4:5]
	v_ashrrev_i32_e32 v7, 31, v6
	v_lshlrev_b64 v[92:93], 12, v[80:81]
	v_ashrrev_i32_e32 v83, 31, v82
	v_lshl_add_u64 v[4:5], v[2:3], 0, v[96:97]
	v_lshlrev_b64 v[94:95], 12, v[6:7]
	v_lshl_add_u64 v[80:81], v[2:3], 0, v[92:93]
	v_lshlrev_b64 v[82:83], 12, v[82:83]
	v_lshl_add_u64 v[6:7], v[2:3], 0, v[94:95]
	v_lshl_add_u64 v[2:3], v[2:3], 0, v[82:83]
	global_load_dwordx2 v[132:133], v[4:5], off
	global_load_dwordx2 v[128:129], v[6:7], off
	global_load_dwordx2 v[126:127], v[80:81], off
	global_load_dwordx2 v[124:125], v[2:3], off
	v_or_b32_e32 v80, 16, v136
	v_ashrrev_i32_e32 v81, 31, v80
	v_lshl_add_u64 v[100:101], s[26:27], 0, v[108:109]
	v_lshlrev_b64 v[90:91], 1, v[80:81]
	v_lshl_add_u64 v[80:81], v[100:101], 0, v[90:91]
	v_lshl_add_u64 v[100:101], s[26:27], 0, v[104:105]
	v_lshl_add_u64 v[106:107], s[26:27], 0, v[102:103]
	v_lshl_add_u64 v[0:1], v[136:137], 2, s[36:37]
	v_lshl_add_u64 v[100:101], v[100:101], 0, v[90:91]
	v_lshl_add_u64 v[106:107], v[106:107], 0, v[90:91]
	v_lshl_add_u64 v[110:111], s[26:27], 0, v[98:99]
	global_load_dwordx4 v[4:7], v[0:1], off
	s_nop 0
	global_load_dwordx4 v[0:3], v[0:1], off offset:64
	v_lshl_add_u64 v[110:111], v[110:111], 0, v[90:91]
	global_load_dwordx2 v[122:123], v[80:81], off
	global_load_dwordx2 v[120:121], v[100:101], off
	global_load_dwordx2 v[118:119], v[106:107], off
	global_load_dwordx2 v[116:117], v[110:111], off
	v_lshl_add_u64 v[80:81], s[26:27], 0, v[96:97]
	v_lshl_add_u64 v[100:101], s[26:27], 0, v[94:95]
	v_lshl_add_u64 v[106:107], s[26:27], 0, v[92:93]
	v_lshl_add_u64 v[80:81], v[80:81], 0, v[90:91]
	v_lshl_add_u64 v[100:101], v[100:101], 0, v[90:91]
	v_lshl_add_u64 v[106:107], v[106:107], 0, v[90:91]
	v_lshl_add_u64 v[82:83], s[26:27], 0, v[82:83]
	v_lshl_add_u64 v[82:83], v[82:83], 0, v[90:91]
	global_load_dwordx2 v[114:115], v[80:81], off
	global_load_dwordx2 v[110:111], v[100:101], off
	s_nop 0
	global_load_dwordx2 v[106:107], v[106:107], off
	s_nop 0
	global_load_dwordx2 v[100:101], v[82:83], off
	v_or_b32_e32 v80, s22, v142
	v_lshlrev_b32_e32 v80, 2, v80
	global_load_dword v198, v80, s[0:1]
	global_load_dword v197, v80, s[0:1] offset:64
	global_load_dword v196, v80, s[0:1] offset:128
	global_load_dword v195, v80, s[0:1] offset:192
	global_load_dword v194, v80, s[0:1] offset:256
	global_load_dword v193, v80, s[0:1] offset:320
	global_load_dword v192, v80, s[0:1] offset:384
	global_load_dword v113, v80, s[0:1] offset:448
	s_waitcnt vmcnt(42)
	v_add_f32_e32 v76, v76, v77
	v_add_f32_e32 v77, v78, v79
	v_add_f32_e32 v72, v72, v73
	v_add_f32_e32 v73, v74, v75
	v_add_f32_e32 v76, v76, v77
	v_add_f32_e32 v72, v72, v73
	v_add_f32_e32 v72, v76, v72
	ds_bpermute_b32 v73, v145, v72
	s_waitcnt lgkmcnt(0)
	v_add_f32_e32 v72, v72, v73
	ds_bpermute_b32 v73, v146, v72
	s_and_saveexec_b64 s[28:29], s[60:61]
	s_cbranch_execz .LBB0_155
	s_waitcnt lgkmcnt(0)
	v_add_f32_e32 v72, v72, v73
	v_fmamk_f32 v72, v72, 0x3a000000, v235
	s_mov_b32 s22, 0x800000
	v_mul_f32_e32 v73, 0x4b800000, v72
	v_cmp_gt_f32_e32 vcc, s22, v72
	s_nop 1
	v_cndmask_b32_e32 v72, v72, v73, vcc
	v_rsq_f32_e32 v72, v72
	s_nop 0
	v_mul_f32_e32 v73, 0x45800000, v72
	v_cndmask_b32_e32 v72, v72, v73, vcc
	ds_write_b32 v147, v72
	s_branch .LBB0_155
